# transposer f32 weight loads marked nt (read-once stream)
# speedup vs baseline: 1.0478x; 1.0029x over previous
; #define LAS __attribute__((address_space(3)))
; __device__ __forceinline__ void transpose_item(const float* W, const float* g  , int K, int N, bf16* WT, LAS float* scr, int kb, int nb, int lane) {
;     const int k0 = 64 * kb, n0 = 32 * nb;
; #pragma unroll 8
;     for (int i = 0; i < 32; ++i) { const int kk = 2 * i + (lane >> 5); const float gv = g ? g[k0 + kk] : 1.f; scr[kk * 33 + (lane & 31)] = W[(size_t)(k0 + kk) * N + n0 + (lane & 31)] * gv; }
.Lwt_run:
	s_load_dwordx2 s[38:39], s[10:11], s19
	s_load_dwordx2 s[40:41], s[10:11], s20
	s_lshr_b32 s27, s63, 5
	s_lshr_b32 s25, s62, 6
	s_mul_i32 s25, s25, s27
	s_mul_i32 s24, s25, s64
	s_lshl_b32 s30, s63, 8
	s_mul_i32 s29, s62, s63
	s_lshl_b32 s31, s29, 1
	s_lshl_b32 s29, s29, 2
	s_lshl_b32 s32, s62, 6
	s_lshl_b32 s35, s63, 2
	s_lshl_b32 s36, s62, 1
	s_add_u32 s42, s12, s34
	s_addc_u32 s43, s13, 0
	v_mad_u32_u24 v110, v102, s35, v109
	s_lshl_b32 s61, s35, 1
	v_add_u32_e32 v111, s61, v110
	v_add_u32_e32 v112, s61, v111
	v_add_u32_e32 v113, s61, v112
	v_add_u32_e32 v114, s61, v113
	v_add_u32_e32 v115, s61, v114
	v_add_u32_e32 v116, s61, v115
	v_add_u32_e32 v117, s61, v116
	v_add_u32_e32 v118, s61, v117
	v_add_u32_e32 v119, s61, v118
	v_add_u32_e32 v120, s61, v119
	v_add_u32_e32 v121, s61, v120
	v_add_u32_e32 v122, s61, v121
	v_add_u32_e32 v123, s61, v122
	v_add_u32_e32 v124, s61, v123
	v_add_u32_e32 v125, s61, v124
	v_add_u32_e32 v126, s61, v125
	v_add_u32_e32 v127, s61, v126
	v_add_u32_e32 v128, s61, v127
	v_add_u32_e32 v129, s61, v128
	v_add_u32_e32 v130, s61, v129
	v_add_u32_e32 v131, s61, v130
	v_add_u32_e32 v132, s61, v131
	v_add_u32_e32 v133, s61, v132
	v_add_u32_e32 v134, s61, v133
	v_add_u32_e32 v135, s61, v134
	v_add_u32_e32 v136, s61, v135
	v_add_u32_e32 v137, s61, v136
	v_add_u32_e32 v138, s61, v137
	v_add_u32_e32 v139, s61, v138
	v_add_u32_e32 v140, s61, v139
	v_add_u32_e32 v141, s61, v140
	v_mad_u32_u24 v142, v106, s36, v105
	s_lshl_b32 s61, s36, 3
	v_add_u32_e32 v143, s61, v142
	v_add_u32_e32 v144, s61, v143
	v_add_u32_e32 v145, s61, v144
	v_mov_b32_e32 v178, 1.0
	v_mov_b32_e32 v179, 1.0
	v_mov_b32_e32 v180, 1.0
	v_mov_b32_e32 v181, 1.0
	v_mov_b32_e32 v182, 1.0
	v_mov_b32_e32 v183, 1.0
	v_mov_b32_e32 v184, 1.0
	v_mov_b32_e32 v185, 1.0
	s_mov_b32 s37, s15
	s_waitcnt lgkmcnt(0)
	s_add_u32 s40, s40, s21
	s_addc_u32 s41, s41, 0
	s_cmp_lt_u32 s37, s24
	s_cbranch_scc0 .Lwt_next
	s_mul_hi_u32 s54, s37, s26
	s_mul_i32 s55, s54, s25
	s_sub_u32 s55, s37, s55
	s_mul_hi_u32 s56, s55, s28
	s_mul_i32 s57, s56, s27
	s_sub_u32 s57, s55, s57
	s_mul_i32 s58, s54, s29
	s_mul_i32 s61, s56, s30
	s_add_u32 s58, s58, s61
	s_lshl_b32 s61, s57, 7
	s_add_u32 s58, s58, s61
	s_add_u32 s44, s38, s58
	s_addc_u32 s45, s39, 0
	s_mul_i32 s58, s54, s31
	s_mul_i32 s61, s57, s32
	s_add_u32 s58, s58, s61
	s_lshl_b32 s61, s56, 7
	s_add_u32 s58, s58, s61
	s_add_u32 s50, s42, s58
	s_addc_u32 s51, s43, 0
	s_mul_i32 s58, s54, s22
	s_lshl_b32 s61, s56, 8
	s_add_u32 s58, s58, s61
	s_add_u32 s48, s40, s58
	s_addc_u32 s49, s41, 0
	global_load_dword v146, v110, s[44:45] nt
	global_load_dword v147, v111, s[44:45] nt
	global_load_dword v148, v112, s[44:45] nt
	global_load_dword v149, v113, s[44:45] nt
	global_load_dword v150, v114, s[44:45] nt
	global_load_dword v151, v115, s[44:45] nt
	global_load_dword v152, v116, s[44:45] nt
	global_load_dword v153, v117, s[44:45] nt
	global_load_dword v154, v118, s[44:45] nt
	global_load_dword v155, v119, s[44:45] nt
	global_load_dword v156, v120, s[44:45] nt
	global_load_dword v157, v121, s[44:45] nt
	global_load_dword v158, v122, s[44:45] nt
	global_load_dword v159, v123, s[44:45] nt
	global_load_dword v160, v124, s[44:45] nt
	global_load_dword v161, v125, s[44:45] nt
	global_load_dword v162, v126, s[44:45] nt
	global_load_dword v163, v127, s[44:45] nt
	global_load_dword v164, v128, s[44:45] nt
	global_load_dword v165, v129, s[44:45] nt
	global_load_dword v166, v130, s[44:45] nt
	global_load_dword v167, v131, s[44:45] nt
	global_load_dword v168, v132, s[44:45] nt
	global_load_dword v169, v133, s[44:45] nt
	global_load_dword v170, v134, s[44:45] nt
	global_load_dword v171, v135, s[44:45] nt
	global_load_dword v172, v136, s[44:45] nt
	global_load_dword v173, v137, s[44:45] nt
	global_load_dword v174, v138, s[44:45] nt
	global_load_dword v175, v139, s[44:45] nt
	global_load_dword v176, v140, s[44:45] nt
	global_load_dword v177, v141, s[44:45] nt
	s_cmp_eq_u32 s23, 0
	s_cbranch_scc1 .Lwt_nog_a
	global_load_dwordx4 v[178:181], v108, s[48:49]
	global_load_dwordx4 v[182:185], v108, s[48:49] offset:16

; #define LDS_WAIT() asm volatile("s_waitcnt lgkmcnt(0)" ::: "memory")
; __device__ __forceinline__ void transpose_item(const float* W, const float* g  , int K, int N, bf16* WT, LAS float* scr, int kb, int nb, int lane) {
;     ...
;     for (int i = 0; i < 32; ++i) { const int kk = 2 * i + (lane >> 5); const float gv = g ? g[k0 + kk] : 1.f; scr[kk * 33 + (lane & 31)] = W[(size_t)(k0 + kk) * N + n0 + (lane & 31)] * gv; }
;     LDS_WAIT(); asm volatile("" ::: "memory");
.Lwt_loop:
	v_mov_b32_e32 v186, v178
	v_mov_b32_e32 v187, v179
	v_mov_b32_e32 v188, v180
	v_mov_b32_e32 v189, v181
	v_mov_b32_e32 v190, v182
	v_mov_b32_e32 v191, v183
	v_mov_b32_e32 v192, v184
	v_mov_b32_e32 v193, v185
	ds_write_b32 v104, v146
	ds_write_b32 v104, v147 offset:264
	ds_write_b32 v104, v148 offset:528
	ds_write_b32 v104, v149 offset:792
	ds_write_b32 v104, v150 offset:1056
	ds_write_b32 v104, v151 offset:1320
	ds_write_b32 v104, v152 offset:1584
	ds_write_b32 v104, v153 offset:1848
	ds_write_b32 v104, v154 offset:2112
	ds_write_b32 v104, v155 offset:2376
	ds_write_b32 v104, v156 offset:2640
	ds_write_b32 v104, v157 offset:2904
	ds_write_b32 v104, v158 offset:3168
	ds_write_b32 v104, v159 offset:3432
	ds_write_b32 v104, v160 offset:3696
	ds_write_b32 v104, v161 offset:3960
	ds_write_b32 v104, v162 offset:4224
	ds_write_b32 v104, v163 offset:4488
	ds_write_b32 v104, v164 offset:4752
	ds_write_b32 v104, v165 offset:5016
	ds_write_b32 v104, v166 offset:5280
	ds_write_b32 v104, v167 offset:5544
	ds_write_b32 v104, v168 offset:5808
	ds_write_b32 v104, v169 offset:6072
	ds_write_b32 v104, v170 offset:6336
	ds_write_b32 v104, v171 offset:6600
	ds_write_b32 v104, v172 offset:6864
	ds_write_b32 v104, v173 offset:7128
	ds_write_b32 v104, v174 offset:7392
	ds_write_b32 v104, v175 offset:7656
	ds_write_b32 v104, v176 offset:7920
	ds_write_b32 v104, v177 offset:8184
	s_mov_b64 s[52:53], s[50:51]
	s_add_u32 s37, s37, s16
	s_cmp_lt_u32 s37, s24
	s_cbranch_scc0 .Lwt_noissue
	s_waitcnt lgkmcnt(0)
	s_mul_hi_u32 s54, s37, s26
	s_mul_i32 s55, s54, s25
	s_sub_u32 s55, s37, s55
	s_mul_hi_u32 s56, s55, s28
	s_mul_i32 s57, s56, s27
	s_sub_u32 s57, s55, s57
	s_mul_i32 s58, s54, s29
	s_mul_i32 s61, s56, s30
	s_add_u32 s58, s58, s61
	s_lshl_b32 s61, s57, 7
	s_add_u32 s58, s58, s61
	s_add_u32 s44, s38, s58
	s_addc_u32 s45, s39, 0
	s_mul_i32 s58, s54, s31
	s_mul_i32 s61, s57, s32
	s_add_u32 s58, s58, s61
	s_lshl_b32 s61, s56, 7
	s_add_u32 s58, s58, s61
	s_add_u32 s50, s42, s58
	s_addc_u32 s51, s43, 0
	s_mul_i32 s58, s54, s22
	s_lshl_b32 s61, s56, 8
	s_add_u32 s58, s58, s61
	s_add_u32 s48, s40, s58
	s_addc_u32 s49, s41, 0
	global_load_dword v146, v110, s[44:45] nt
	global_load_dword v147, v111, s[44:45] nt
	global_load_dword v148, v112, s[44:45] nt
	global_load_dword v149, v113, s[44:45] nt
	global_load_dword v150, v114, s[44:45] nt
	global_load_dword v151, v115, s[44:45] nt
	global_load_dword v152, v116, s[44:45] nt
	global_load_dword v153, v117, s[44:45] nt
	global_load_dword v154, v118, s[44:45] nt
	global_load_dword v155, v119, s[44:45] nt
	global_load_dword v156, v120, s[44:45] nt
	global_load_dword v157, v121, s[44:45] nt
	global_load_dword v158, v122, s[44:45] nt
	global_load_dword v159, v123, s[44:45] nt
	global_load_dword v160, v124, s[44:45] nt
	global_load_dword v161, v125, s[44:45] nt
	global_load_dword v162, v126, s[44:45] nt
	global_load_dword v163, v127, s[44:45] nt
	global_load_dword v164, v128, s[44:45] nt
	global_load_dword v165, v129, s[44:45] nt
	global_load_dword v166, v130, s[44:45] nt
	global_load_dword v167, v131, s[44:45] nt
	global_load_dword v168, v132, s[44:45] nt
	global_load_dword v169, v133, s[44:45] nt
	global_load_dword v170, v134, s[44:45] nt
	global_load_dword v171, v135, s[44:45] nt
	global_load_dword v172, v136, s[44:45] nt
	global_load_dword v173, v137, s[44:45] nt
	global_load_dword v174, v138, s[44:45] nt
	global_load_dword v175, v139, s[44:45] nt
	global_load_dword v176, v140, s[44:45] nt
	global_load_dword v177, v141, s[44:45] nt
	s_cmp_eq_u32 s23, 0
	s_cbranch_scc1 .Lwt_nog_b
	global_load_dwordx4 v[178:181], v108, s[48:49]
	global_load_dwordx4 v[182:185], v108, s[48:49] offset:16
